# split grid sync: the kernel-start cooperative sync posts its arrival at entry and P0 starts at once; the wait for its release moved to the end of P0, in front of the XCC census post (the first atomic
# speedup vs baseline: 1.0068x; 1.0068x over previous
; __device__ __forceinline__ int lane_id_asm() { int l; asm volatile("v_mbcnt_lo_u32_b32 %0, -1, 0\n\tv_mbcnt_hi_u32_b32 %0, -1, %0" : "=v"(l)); return l; }
; #define GAS __attribute__((address_space(1)))
; #define LAS __attribute__((address_space(3)))
; __device__ __forceinline__ unsigned xb_add(unsigned* p, unsigned v) { return __hip_atomic_fetch_add(p, v, __ATOMIC_RELAXED, __HIP_MEMORY_SCOPE_AGENT); }
; __device__ __forceinline__ unsigned xb_xcc_id() { return (unsigned)__builtin_amdgcn_s_getreg((3 << 11) | 20) & 0xFu; }
; __device__ __forceinline__ XcdBarrier xcd_barrier_post(unsigned* bar, volatile LAS unsigned* st, const int wid) {
;     XcdBarrier b; b.bar = bar; b.x = xb_xcc_id(); b.st = st;
;     if (wid == 0 && lane_id_asm() == 0) (void)xb_add(&bar[XB_XCNT(b.x)], 1u);
;     return b;
; __global__ void __launch_bounds__(NWAVES * 64, 2) hybrid_fwd(const Args A) {
;     ...
;     if (hi - lo > 1) {
;         if (blockIdx.x == 0) { GAS v4u* z = (GAS v4u*)(F.ws + WS_CTL); for (int i = F.tid; i < (int)(CTL_ZERO_BYTES / 16); i += NWAVES * 64) if (i < (int)(WS_PRM / 16) || i >= (int)((CW_SEAM * 4) / 16)) z[i] = (v4u){0u, 0u, 0u, 0u}; }
;         grid.sync();
;         bar = xcd_barrier_post(F.ctl + CW_BAR, MISC + 8, F.wave);
.LBB0_16:
	s_or_b64 exec, exec, s[6:7]
	v_and_b32_e32 v1, 0xffff0000, v1
	v_mov_b32_e32 v0, 0x25730
	ds_write_b32 v0, v1
	s_waitcnt lgkmcnt(0)
.LBB0_19:
.LBB0_20:
	s_or_b64 exec, exec, s[4:5]
	s_barrier
	s_getreg_b32 s2, hwreg(HW_REG_XCC_ID, 0, 4)
	s_and_b32 s2, s2, 15
	v_writelane_b32 v254, s2, 8
.LBB0_25:
	s_add_i32 s5, 0, 0x25720

; __device__ __forceinline__ int lane_id_asm() { int l; asm volatile("v_mbcnt_lo_u32_b32 %0, -1, 0\n\tv_mbcnt_hi_u32_b32 %0, -1, %0" : "=v"(l)); return l; }
; #define LAS __attribute__((address_space(3)))
; __device__ __forceinline__ unsigned xb_add(unsigned* p, unsigned v) { return __hip_atomic_fetch_add(p, v, __ATOMIC_RELAXED, __HIP_MEMORY_SCOPE_AGENT); }
; __device__ __forceinline__ unsigned xb_xcc_id() { return (unsigned)__builtin_amdgcn_s_getreg((3 << 11) | 20) & 0xFu; }
; __device__ __forceinline__ XcdBarrier xcd_barrier_post(unsigned* bar, volatile LAS unsigned* st, const int wid) {
;     XcdBarrier b; b.bar = bar; b.x = xb_xcc_id(); b.st = st;
;     if (wid == 0 && lane_id_asm() == 0) (void)xb_add(&bar[XB_XCNT(b.x)], 1u);
;     return b;
; __device__ __forceinline__ void xcd_barrier(const XcdBarrier& b, const int wid) {
;     asm volatile("s_waitcnt vmcnt(0)" ::: "memory");
;     __syncthreads();
;     if (wid == 0 && lane_id_asm() == 0) {
;         unsigned* bar = b.bar;
;         __builtin_amdgcn_s_waitcnt(0);
;         unsigned nloc = b.st[0], nx = b.st[1];
;         if (nloc == 0u) { xcd_barrier_complete(bar, b.x, nloc, nx); b.st[0] = nloc; b.st[1] = nx; }
;         const unsigned old = xb_add(&bar[XB_XSUB(b.x)], 1u);
.LBB0_207:
	v_cndmask_b32_e64 v0, 0, 1, s[0:1]
	v_cmp_ne_u32_e64 s[2:3], 1, v0
	s_andn2_b64 vcc, exec, s[0:1]
	s_nop 0
	v_writelane_b32 v254, s2, 13
	s_nop 1
	v_writelane_b32 v254, s3, 14
	s_cbranch_vccnz .LBB0_259
	s_waitcnt vmcnt(0)
	s_cmp_gt_u32 s79, 63
	s_barrier
	s_cbranch_scc1 .LBB0_258
	v_mbcnt_lo_u32_b32 v0, -1, 0
	v_mbcnt_hi_u32_b32 v0, -1, v0
	s_nop 0
	v_cmp_eq_u32_e32 vcc, 0, v0
	s_and_saveexec_b64 s[0:1], vcc
	s_cbranch_execz .LBB0_257
	v_mov_b32_e32 v2, 0x25730
	ds_read_b32 v1, v2
	s_add_u32 s2, s72, 0x110
	s_addc_u32 s3, s73, 0
	s_load_dwordx2 s[2:3], s[2:3], 0x58
	v_mov_b32_e32 v0, 0
	s_waitcnt lgkmcnt(0)
.Lcg_spin:
	global_load_dword v2, v0, s[2:3] offset:32 sc1
	s_waitcnt vmcnt(0)
	v_and_b32_e32 v2, 0xffff0000, v2
	v_cmp_ne_u32_e32 vcc, v2, v1
	s_cbranch_vccnz .Lcg_out
	s_sleep 1
	s_branch .Lcg_spin
.Lcg_out:
	v_readlane_b32 s6, v254, 8
	s_lshl_b32 s6, s6, 8
	v_readlane_b32 s4, v254, 6
	v_readlane_b32 s5, v254, 7
	v_mov_b32_e32 v0, s6
	v_mov_b32_e32 v1, 1
	s_nop 4
	global_atomic_add v0, v1, s[4:5] offset:1024
	v_readlane_b32 s2, v254, 9
	s_waitcnt vmcnt(0) expcnt(0) lgkmcnt(0)
	s_nop 0
	v_mov_b32_e32 v0, s2
	ds_read_b32 v2, v0
	ds_read_b32 v0, v0 offset:4
	s_waitcnt lgkmcnt(1)
	v_cmp_ne_u32_e32 vcc, 0, v2
	s_cbranch_vccnz .LBB0_225
	v_readlane_b32 s2, v254, 4
	v_readlane_b32 s3, v254, 5
	s_mul_i32 s33, s3, s77
	s_mul_i32 s33, s33, s2
	s_add_u32 s2, s86, 0x4200
	s_addc_u32 s3, s87, 0
	s_add_u32 s4, s86, 0x4400
	s_addc_u32 s5, s87, 0
	s_add_u32 s6, s86, 0x4500
	s_addc_u32 s7, s87, 0
	s_add_u32 s8, s86, 0x4600
	s_addc_u32 s9, s87, 0
	s_add_u32 s10, s86, 0x4700
	s_addc_u32 s11, s87, 0
	s_add_u32 s12, s86, 0x4800
	s_addc_u32 s13, s87, 0
	s_add_u32 s14, s86, 0x4900
	s_addc_u32 s15, s87, 0
	s_add_u32 s16, s86, 0x4a00
	s_addc_u32 s17, s87, 0
	s_add_u32 s18, s86, 0x4b00
	s_addc_u32 s19, s87, 0
	s_add_u32 s20, s86, 0x4c00
	s_addc_u32 s21, s87, 0
	s_add_u32 s22, s86, 0x4d00
	s_addc_u32 s23, s87, 0
	s_add_u32 s24, s86, 0x4e00
	s_addc_u32 s25, s87, 0
	s_add_u32 s26, s86, 0x4f00
	s_addc_u32 s27, s87, 0
	s_add_u32 s28, s86, 0x5000
	s_addc_u32 s29, s87, 0
	s_add_u32 s30, s86, 0x5100
	s_addc_u32 s31, s87, 0
	s_add_u32 s34, s86, 0x5200
	s_addc_u32 s35, s87, 0
	s_add_u32 s38, s86, 0x5300
	s_addc_u32 s39, s87, 0
	s_mov_b32 s46, 1
	v_mov_b32_e32 v16, 0
	s_branch .LBB0_213
